# gla chain loader paced with 8 x s_sleep 1 per step
# baseline (speedup 1.0000x reference)
; #define LBAR() do { asm volatile("s_waitcnt lgkmcnt(0)" ::: "memory"); __builtin_amdgcn_s_barrier(); asm volatile("" ::: "memory"); } while (0)
; #define WAITV(N_) asm volatile("s_waitcnt vmcnt(" #N_ ")" ::: "memory")
; #define ISSUE_XG(s_) do { const unsigned char* g_ = A.blob + (unit0 + CHUNK_OF(s_)) * BLOB + lane * 16; const unsigned l_ = lds0 + ((s_) & 1) * C_BUF; \
;         _Pragma("unroll") for (int k = 0; k < 8; ++k) { const unsigned o_ = (lw + 4 * k) * 1024; DMA1(g_ + o_, l_ + o_); __builtin_amdgcn_s_sleep(LOADER_PACE); } } while (0)
; #define WAITV(N_) asm volatile("s_waitcnt vmcnt(" #N_ ")" ::: "memory")
; #define ISSUE_XG(s_) do { const unsigned char* g_ = A.blobA + (unit0 + CHUNK_OF(s_)) * BLOBA + qo + lane * 16; const unsigned l_ = lds0 + ((s_) & 1) * CB_BUF; \
;         _Pragma("unroll") for (int k = 0; k < 4; ++k) { const unsigned o_ = (lw + 4 * k) * 1024; DMA1(g_ + o_, l_ + o_); } } while (0)
; __device__ __forceinline__ void gla_chain_unit(LAS unsigned char* lds, const GlaChainArgs& A, int item, int half) {
;     ...
;         if (!(flags & 4)) { ISSUE_XG(0); ISSUE_YG(0); ISSUE_XG(1); }
;         WAITV(0);
;         LBAR();
;         for (int s = 0; s < NCH; ++s) {
;             if (s + 1 < NCH && !(flags & 4)) ISSUE_YG(s + 1);
.LBB0_623:
	s_add_i32 s44, s45, 1
	s_and_b64 s[2:3], s[52:53], exec
	s_cselect_b32 s2, s44, s43
	s_add_i32 s34, s2, s60
	v_mad_u64_u32 v[8:9], s[2:3], s34, v171, v[2:3]
	s_lshl_b64 s[2:3], s[34:35], 16
	s_bitcmp1_b32 s44, 0
	v_readlane_b32 s46, v252, 48
	s_cselect_b32 s34, s42, 0
	v_readlane_b32 s47, v252, 49
	v_lshl_add_u64 v[10:11], v[4:5], 0, s[2:3]
	s_add_i32 s3, s34, 0x4400
	v_lshl_add_u64 v[12:13], v[8:9], 0, s[46:47]
	v_lshl_add_u64 v[14:15], v[12:13], 0, s[4:5]
	s_add_i32 s46, s3, s4
	s_mov_b32 m0, s46
	s_nop 0
	global_load_lds_dwordx4 v[14:15], off
	s_sleep 1
	v_lshl_add_u64 v[14:15], v[12:13], 0, s[6:7]
	s_add_i32 s46, s3, s6
	s_mov_b32 m0, s46
	s_nop 0
	global_load_lds_dwordx4 v[14:15], off
	s_sleep 1
	v_lshl_add_u64 v[14:15], v[12:13], 0, s[36:37]
	s_add_i32 s46, s3, s36
	s_mov_b32 m0, s46
	s_nop 0
	global_load_lds_dwordx4 v[14:15], off
	s_sleep 1
	s_add_i32 s2, s34, 0x8400
	v_lshl_add_u64 v[12:13], v[12:13], 0, s[38:39]
	s_add_i32 s3, s3, s38
	s_mov_b32 m0, s3
	s_nop 0
	global_load_lds_dwordx4 v[12:13], off
	s_sleep 1
	v_lshl_add_u64 v[12:13], v[10:11], 0, s[4:5]
	s_add_i32 s3, s2, s4
	s_mov_b32 m0, s3
	s_nop 0
	global_load_lds_dwordx4 v[12:13], off
	s_sleep 1
	v_lshl_add_u64 v[12:13], v[10:11], 0, s[6:7]
	s_add_i32 s3, s2, s6
	s_mov_b32 m0, s3
	s_nop 0
	global_load_lds_dwordx4 v[12:13], off
	s_sleep 1
	v_lshl_add_u64 v[12:13], v[10:11], 0, s[36:37]
	s_add_i32 s3, s2, s36
	s_mov_b32 m0, s3
	s_nop 0
	global_load_lds_dwordx4 v[12:13], off
	s_sleep 1
	v_lshl_add_u64 v[10:11], v[10:11], 0, s[38:39]
	s_add_i32 s46, s2, s38
	s_mov_b32 m0, s46
	s_nop 0
	global_load_lds_dwordx4 v[10:11], off
	s_sleep 1
	v_cndmask_b32_e64 v12, 0, 1, s[40:41]
	v_cmp_ne_u32_e64 s[2:3], 1, v12
	s_andn2_b64 vcc, exec, s[40:41]
	s_cbranch_vccnz .LBB0_622
	s_mov_b64 s[46:47], 0x8000
	v_lshl_add_u64 v[8:9], v[8:9], 0, s[46:47]
	s_addk_i32 s34, 0x4000
	s_mov_b32 m0, s34
	s_nop 0
	global_load_lds_dwordx4 v[8:9], off
	s_branch .LBB0_622
